# moba-loop-tiles-fixed-softmax-reference+leader-early-inv
# speedup vs baseline: 1.0393x; 1.0112x over previous
.LBB0_76:
	s_or_b64 exec, exec, s[40:41]
	v_cmp_lt_i32_e64 s[40:41], -1, v140
	s_nop 3
	v_cndmask_b32_e64 v169, v236, v142, s[40:41]
	v_cndmask_b32_e64 v169, v169, v142, s[36:37]
.LBB0_78:
	v_sub_f32_e32 v80, v80, v169
	v_exp_f32_e32 v171, v80
	v_sub_f32_e32 v81, v81, v169
	v_sub_f32_e32 v69, v69, v169
	v_exp_f32_e32 v81, v81
	v_sub_f32_e32 v82, v82, v169
	v_exp_f32_e32 v173, v69
	v_sub_f32_e32 v69, v70, v169
	v_exp_f32_e32 v82, v82
	v_sub_f32_e32 v83, v83, v169
	v_exp_f32_e32 v174, v69
	v_sub_f32_e32 v69, v71, v169
	v_exp_f32_e32 v83, v83
	v_sub_f32_e32 v84, v84, v169
	v_exp_f32_e32 v71, v69
	v_sub_f32_e32 v69, v72, v169
	v_add_f32_e32 v80, 0, v171
	v_exp_f32_e32 v84, v84
	v_sub_f32_e32 v85, v85, v169
	v_exp_f32_e32 v175, v69
	v_sub_f32_e32 v69, v73, v169
	v_add_f32_e32 v80, v81, v80
	v_exp_f32_e32 v85, v85
	v_sub_f32_e32 v86, v86, v169
	v_sub_f32_e32 v87, v87, v169
	v_exp_f32_e32 v176, v69
	v_sub_f32_e32 v69, v74, v169
	v_add_f32_e32 v80, v82, v80
	v_exp_f32_e32 v86, v86
	v_exp_f32_e32 v87, v87
	v_exp_f32_e32 v177, v69
	v_sub_f32_e32 v69, v75, v169
	v_add_f32_e32 v80, v83, v80
	v_exp_f32_e32 v178, v69
	v_sub_f32_e32 v69, v76, v169
	v_add_f32_e32 v80, v84, v80
	v_exp_f32_e32 v179, v69
	v_sub_f32_e32 v69, v77, v169
	v_cvt_pk_bf16_f32 v76, v171, v81
	v_add_f32_e32 v80, v85, v80
	v_exp_f32_e32 v180, v69
	v_sub_f32_e32 v69, v78, v169
	v_add_f32_e32 v80, v86, v80
	v_exp_f32_e32 v181, v69
	v_sub_f32_e32 v69, v79, v169
	v_cvt_pk_bf16_f32 v79, v86, v87
	v_cvt_pk_bf16_f32 v77, v82, v83
	v_cvt_pk_bf16_f32 v78, v84, v85
	v_add_f32_e32 v80, v87, v80
	v_sub_f32_e32 v88, v88, v169
	v_sub_f32_e32 v89, v89, v169
	v_exp_f32_e32 v88, v88
	v_exp_f32_e32 v89, v89
	s_waitcnt lgkmcnt(14)
	v_mfma_f32_32x32x16_bf16 v[48:63], v[188:191], v[76:79], v[48:63]
	ds_read_b64_tr_b16 v[188:189], v183 offset:24576
	ds_read_b64_tr_b16 v[190:191], v183 offset:26624
	v_add_f32_e32 v80, v88, v80
	v_cvt_pk_bf16_f32 v72, v88, v89
	v_sub_f32_e32 v90, v90, v169
	v_exp_f32_e32 v90, v90
	s_waitcnt lgkmcnt(14)
	v_mfma_f32_32x32x16_bf16 v[32:47], v[192:195], v[76:79], v[32:47]
	ds_read_b64_tr_b16 v[192:193], v184 offset:24576
	ds_read_b64_tr_b16 v[194:195], v184 offset:26624
	v_sub_f32_e32 v91, v91, v169
	v_sub_f32_e32 v92, v92, v169
	v_sub_f32_e32 v93, v93, v169
	v_sub_f32_e32 v94, v94, v169
	v_sub_f32_e32 v95, v95, v169
	v_exp_f32_e32 v91, v91
	s_waitcnt lgkmcnt(14)
	v_mfma_f32_32x32x16_bf16 v[16:31], v[198:201], v[76:79], v[16:31]
	ds_read_b64_tr_b16 v[198:199], v185 offset:24576
	ds_read_b64_tr_b16 v[200:201], v185 offset:26624
	v_exp_f32_e32 v92, v92
	v_exp_f32_e32 v93, v93
	v_exp_f32_e32 v94, v94
	v_exp_f32_e32 v95, v95
	v_add_f32_e32 v80, v89, v80
	v_add_f32_e32 v80, v90, v80
	s_waitcnt lgkmcnt(14)
	v_mfma_f32_32x32x16_bf16 v[0:15], v[202:205], v[76:79], v[0:15]
	ds_read_b64_tr_b16 v[202:203], v186 offset:24576
	ds_read_b64_tr_b16 v[204:205], v186 offset:26624
	v_add_f32_e32 v80, v91, v80
	v_sub_f32_e32 v64, v64, v169
	v_cvt_pk_bf16_f32 v73, v90, v91
	v_cvt_pk_bf16_f32 v74, v92, v93
	v_cvt_pk_bf16_f32 v75, v94, v95
	v_add_f32_e32 v80, v92, v80
	v_exp_f32_e32 v64, v64
	v_sub_f32_e32 v65, v65, v169
	s_waitcnt lgkmcnt(14)
	v_mfma_f32_32x32x16_bf16 v[48:63], v[206:209], v[72:75], v[48:63]
	ds_read_b64_tr_b16 v[206:207], v183 offset:28672
	ds_read_b64_tr_b16 v[208:209], v183 offset:30720
	v_add_f32_e32 v80, v93, v80
	v_exp_f32_e32 v65, v65
	v_sub_f32_e32 v66, v66, v169
	v_add_f32_e32 v80, v94, v80
	v_exp_f32_e32 v66, v66
	v_sub_f32_e32 v67, v67, v169
	v_add_f32_e32 v80, v95, v80
	v_exp_f32_e32 v67, v67
	v_sub_f32_e32 v68, v68, v169
	v_add_f32_e32 v80, v64, v80
	v_exp_f32_e32 v172, v68
	v_add_f32_e32 v80, v65, v80
	s_waitcnt lgkmcnt(14)
	v_mfma_f32_32x32x16_bf16 v[32:47], v[210:213], v[72:75], v[32:47]
	ds_read_b64_tr_b16 v[210:211], v184 offset:28672
	ds_read_b64_tr_b16 v[212:213], v184 offset:30720
	v_add_f32_e32 v80, v66, v80
	v_add_f32_e32 v80, v67, v80
	v_add_f32_e32 v68, v172, v80
	v_add_f32_e32 v68, v173, v68
	v_add_f32_e32 v68, v174, v68
	v_add_f32_e32 v68, v71, v68
	s_waitcnt lgkmcnt(14)
	v_mfma_f32_32x32x16_bf16 v[16:31], v[214:217], v[72:75], v[16:31]
	ds_read_b64_tr_b16 v[214:215], v185 offset:28672
	ds_read_b64_tr_b16 v[216:217], v185 offset:30720
	v_add_f32_e32 v68, v175, v68
	v_add_f32_e32 v68, v176, v68
	v_add_f32_e32 v68, v177, v68
	v_add_f32_e32 v68, v178, v68
	v_exp_f32_e32 v182, v69
	v_add_f32_e32 v68, v179, v68
	s_waitcnt lgkmcnt(14)
	v_mfma_f32_32x32x16_bf16 v[0:15], v[218:221], v[72:75], v[0:15]
	ds_read_b64_tr_b16 v[218:219], v186 offset:28672
	ds_read_b64_tr_b16 v[220:221], v186 offset:30720
	v_add_f32_e32 v68, v180, v68
	v_add_f32_e32 v68, v181, v68
	v_add_f32_e32 v80, v182, v68
	v_cvt_pk_bf16_f32 v68, v64, v65
	v_cvt_pk_bf16_f32 v69, v66, v67
	v_cvt_pk_bf16_f32 v70, v172, v173
	v_cvt_pk_bf16_f32 v71, v174, v71
	v_cvt_pk_bf16_f32 v64, v175, v176
	v_cvt_pk_bf16_f32 v65, v177, v178
	s_waitcnt lgkmcnt(14)
	v_mfma_f32_32x32x16_bf16 v[48:63], v[188:191], v[68:71], v[48:63]
	v_cvt_pk_bf16_f32 v66, v179, v180
	v_cvt_pk_bf16_f32 v67, v181, v182
	v_add_f32_e32 v80, v168, v80
	v_mov_b32_e32 v168, v80
	s_waitcnt lgkmcnt(12)
	v_mfma_f32_32x32x16_bf16 v[32:47], v[192:195], v[68:71], v[32:47]
	s_waitcnt lgkmcnt(10)
	v_mfma_f32_32x32x16_bf16 v[16:31], v[198:201], v[68:71], v[16:31]
	s_waitcnt lgkmcnt(8)
	v_mfma_f32_32x32x16_bf16 v[0:15], v[202:205], v[68:71], v[0:15]
	s_waitcnt lgkmcnt(6)
	v_mfma_f32_32x32x16_bf16 v[48:63], v[206:209], v[64:67], v[48:63]
	s_waitcnt lgkmcnt(4)
	v_mfma_f32_32x32x16_bf16 v[32:47], v[210:213], v[64:67], v[32:47]
	s_waitcnt lgkmcnt(2)
	v_mfma_f32_32x32x16_bf16 v[16:31], v[214:217], v[64:67], v[16:31]
	s_waitcnt lgkmcnt(0)
	v_mfma_f32_32x32x16_bf16 v[0:15], v[218:221], v[64:67], v[0:15]

.LBB0_86:
	s_or_b64 exec, exec, s[38:39]
	v_cmp_lt_i32_e64 s[38:39], -1, v133
	s_nop 3
	v_cndmask_b32_e64 v169, v236, v142, s[38:39]
	v_cndmask_b32_e64 v169, v169, v142, s[36:37]
.LBB0_88:
	v_sub_f32_e32 v80, v80, v169
	v_exp_f32_e32 v170, v80
	v_sub_f32_e32 v81, v81, v169
	v_sub_f32_e32 v69, v69, v169
	v_exp_f32_e32 v81, v81
	v_sub_f32_e32 v82, v82, v169
	v_exp_f32_e32 v172, v69
	v_sub_f32_e32 v69, v70, v169
	v_exp_f32_e32 v82, v82
	v_sub_f32_e32 v83, v83, v169
	v_exp_f32_e32 v173, v69
	v_sub_f32_e32 v69, v71, v169
	v_exp_f32_e32 v83, v83
	v_sub_f32_e32 v84, v84, v169
	v_exp_f32_e32 v71, v69
	v_sub_f32_e32 v69, v72, v169
	v_add_f32_e32 v80, 0, v170
	v_exp_f32_e32 v84, v84
	v_sub_f32_e32 v85, v85, v169
	v_exp_f32_e32 v174, v69
	v_sub_f32_e32 v69, v73, v169
	v_add_f32_e32 v80, v81, v80
	v_exp_f32_e32 v85, v85
	v_sub_f32_e32 v86, v86, v169
	v_sub_f32_e32 v87, v87, v169
	v_exp_f32_e32 v175, v69
	v_sub_f32_e32 v69, v74, v169
	v_add_f32_e32 v80, v82, v80
	v_exp_f32_e32 v86, v86
	v_exp_f32_e32 v87, v87
	v_exp_f32_e32 v176, v69
	v_sub_f32_e32 v69, v75, v169
	v_add_f32_e32 v80, v83, v80
	v_exp_f32_e32 v177, v69
	v_sub_f32_e32 v69, v76, v169
	v_add_f32_e32 v80, v84, v80
	v_exp_f32_e32 v178, v69
	v_sub_f32_e32 v69, v77, v169
	v_cvt_pk_bf16_f32 v76, v170, v81
	v_add_f32_e32 v80, v85, v80
	v_exp_f32_e32 v179, v69
	v_sub_f32_e32 v69, v78, v169
	v_add_f32_e32 v80, v86, v80
	v_exp_f32_e32 v180, v69
	v_sub_f32_e32 v69, v79, v169
	v_cvt_pk_bf16_f32 v79, v86, v87
	v_cvt_pk_bf16_f32 v77, v82, v83
	v_cvt_pk_bf16_f32 v78, v84, v85
	v_add_f32_e32 v80, v87, v80
	v_sub_f32_e32 v88, v88, v169
	v_sub_f32_e32 v89, v89, v169
	v_exp_f32_e32 v88, v88
	v_exp_f32_e32 v89, v89
	s_waitcnt lgkmcnt(14)
	v_mfma_f32_32x32x16_bf16 v[48:63], v[188:191], v[76:79], v[48:63]
	ds_read_b64_tr_b16 v[188:189], v183 offset:57344
	ds_read_b64_tr_b16 v[190:191], v183 offset:59392
	v_add_f32_e32 v80, v88, v80
	v_cvt_pk_bf16_f32 v72, v88, v89
	v_sub_f32_e32 v90, v90, v169
	v_exp_f32_e32 v90, v90
	s_waitcnt lgkmcnt(14)
	v_mfma_f32_32x32x16_bf16 v[32:47], v[192:195], v[76:79], v[32:47]
	ds_read_b64_tr_b16 v[192:193], v184 offset:57344
	ds_read_b64_tr_b16 v[194:195], v184 offset:59392
	v_sub_f32_e32 v91, v91, v169
	v_sub_f32_e32 v92, v92, v169
	v_sub_f32_e32 v93, v93, v169
	v_sub_f32_e32 v94, v94, v169
	v_sub_f32_e32 v95, v95, v169
	v_exp_f32_e32 v91, v91
	s_waitcnt lgkmcnt(14)
	v_mfma_f32_32x32x16_bf16 v[16:31], v[198:201], v[76:79], v[16:31]
	ds_read_b64_tr_b16 v[198:199], v185 offset:57344
	ds_read_b64_tr_b16 v[200:201], v185 offset:59392
	v_exp_f32_e32 v92, v92
	v_exp_f32_e32 v93, v93
	v_exp_f32_e32 v94, v94
	v_exp_f32_e32 v95, v95
	v_add_f32_e32 v80, v89, v80
	v_add_f32_e32 v80, v90, v80
	s_waitcnt lgkmcnt(14)
	v_mfma_f32_32x32x16_bf16 v[0:15], v[202:205], v[76:79], v[0:15]
	ds_read_b64_tr_b16 v[202:203], v186 offset:57344
	ds_read_b64_tr_b16 v[204:205], v186 offset:59392
	v_add_f32_e32 v80, v91, v80
	v_sub_f32_e32 v64, v64, v169
	v_cvt_pk_bf16_f32 v73, v90, v91
	v_cvt_pk_bf16_f32 v74, v92, v93
	v_cvt_pk_bf16_f32 v75, v94, v95
	v_add_f32_e32 v80, v92, v80
	v_exp_f32_e32 v64, v64
	v_sub_f32_e32 v65, v65, v169
	s_waitcnt lgkmcnt(14)
	v_mfma_f32_32x32x16_bf16 v[48:63], v[206:209], v[72:75], v[48:63]
	ds_read_b64_tr_b16 v[206:207], v183 offset:61440
	ds_read_b64_tr_b16 v[208:209], v183 offset:63488
	v_add_f32_e32 v80, v93, v80
	v_exp_f32_e32 v65, v65
	v_sub_f32_e32 v66, v66, v169
	v_add_f32_e32 v80, v94, v80
	v_exp_f32_e32 v66, v66
	v_sub_f32_e32 v67, v67, v169
	v_add_f32_e32 v80, v95, v80
	v_exp_f32_e32 v67, v67
	v_sub_f32_e32 v68, v68, v169
	v_add_f32_e32 v80, v64, v80
	v_exp_f32_e32 v171, v68
	v_add_f32_e32 v80, v65, v80
	s_waitcnt lgkmcnt(14)
	v_mfma_f32_32x32x16_bf16 v[32:47], v[210:213], v[72:75], v[32:47]
	ds_read_b64_tr_b16 v[210:211], v184 offset:61440
	ds_read_b64_tr_b16 v[212:213], v184 offset:63488
	v_add_f32_e32 v80, v66, v80
	v_add_f32_e32 v80, v67, v80
	v_add_f32_e32 v68, v171, v80
	v_add_f32_e32 v68, v172, v68
	v_add_f32_e32 v68, v173, v68
	v_add_f32_e32 v68, v71, v68
	s_waitcnt lgkmcnt(14)
	v_mfma_f32_32x32x16_bf16 v[16:31], v[214:217], v[72:75], v[16:31]
	ds_read_b64_tr_b16 v[214:215], v185 offset:61440
	ds_read_b64_tr_b16 v[216:217], v185 offset:63488
	v_add_f32_e32 v68, v174, v68
	v_add_f32_e32 v68, v175, v68
	v_add_f32_e32 v68, v176, v68
	v_add_f32_e32 v68, v177, v68
	v_exp_f32_e32 v181, v69
	v_add_f32_e32 v68, v178, v68
	s_waitcnt lgkmcnt(14)
	v_mfma_f32_32x32x16_bf16 v[0:15], v[218:221], v[72:75], v[0:15]
	ds_read_b64_tr_b16 v[218:219], v186 offset:61440
	ds_read_b64_tr_b16 v[220:221], v186 offset:63488
	v_add_f32_e32 v68, v179, v68
	v_add_f32_e32 v68, v180, v68
	v_add_f32_e32 v80, v181, v68
	v_cvt_pk_bf16_f32 v68, v64, v65
	v_cvt_pk_bf16_f32 v69, v66, v67
	v_cvt_pk_bf16_f32 v70, v171, v172
	v_cvt_pk_bf16_f32 v71, v173, v71
	v_cvt_pk_bf16_f32 v64, v174, v175
	v_cvt_pk_bf16_f32 v65, v176, v177
	s_waitcnt lgkmcnt(14)
	v_mfma_f32_32x32x16_bf16 v[48:63], v[188:191], v[68:71], v[48:63]
	v_cvt_pk_bf16_f32 v66, v178, v179
	v_cvt_pk_bf16_f32 v67, v180, v181
	v_add_f32_e32 v80, v168, v80
	v_mov_b32_e32 v168, v80
	s_waitcnt lgkmcnt(12)
	v_mfma_f32_32x32x16_bf16 v[32:47], v[192:195], v[68:71], v[32:47]
	s_waitcnt lgkmcnt(10)
	v_mfma_f32_32x32x16_bf16 v[16:31], v[198:201], v[68:71], v[16:31]
	s_waitcnt lgkmcnt(8)
	v_mfma_f32_32x32x16_bf16 v[0:15], v[202:205], v[68:71], v[0:15]
	s_waitcnt lgkmcnt(6)
	v_mfma_f32_32x32x16_bf16 v[48:63], v[206:209], v[64:67], v[48:63]
	s_waitcnt lgkmcnt(4)
	v_mfma_f32_32x32x16_bf16 v[32:47], v[210:213], v[64:67], v[32:47]
	s_waitcnt lgkmcnt(2)
	v_mfma_f32_32x32x16_bf16 v[16:31], v[214:217], v[64:67], v[16:31]
	s_waitcnt lgkmcnt(0)
	v_mfma_f32_32x32x16_bf16 v[0:15], v[218:221], v[64:67], v[0:15]

.LBB0_614:
	s_or_b64 exec, exec, s[36:37]
	s_waitcnt vmcnt(0)
	buffer_inv sc1
	v_readfirstlane_b32 s2, v2
	v_cvt_f32_u32_e32 v2, v0
	v_sub_u32_e32 v3, 0, v0
	v_add_u32_e32 v1, s2, v1
	v_readlane_b32 s4, v253, 43
	v_rcp_iflag_f32_e32 v2, v2
	v_readlane_b32 s5, v253, 44
	s_mov_b64 s[36:37], -1
	v_mul_f32_e32 v2, 0x4f7ffffe, v2
	v_cvt_u32_f32_e32 v2, v2
	v_mul_lo_u32 v3, v3, v2
	v_mul_hi_u32 v3, v2, v3
	v_add_u32_e32 v2, v2, v3
	v_mul_hi_u32 v2, v1, v2
	v_mul_lo_u32 v3, v2, v0
	v_sub_u32_e32 v3, v1, v3
	v_cmp_ge_u32_e32 vcc, v3, v0
	v_add_u32_e32 v4, 1, v2
	v_add_u32_e32 v1, 1, v1
	v_cndmask_b32_e32 v2, v2, v4, vcc
	v_sub_u32_e32 v4, v3, v0
	v_cndmask_b32_e32 v3, v3, v4, vcc
	v_cmp_ge_u32_e32 vcc, v3, v0
	v_add_u32_e32 v3, 1, v2
	s_nop 0
	v_cndmask_b32_e32 v2, v2, v3, vcc
	v_mul_lo_u32 v3, v0, v2
	v_add_u32_e32 v0, v3, v0
	v_cmp_ne_u32_e32 vcc, v1, v0
	v_mov_b64_e32 v[0:1], s[4:5]
	s_and_saveexec_b64 s[30:31], vcc
	s_cbranch_execz .Lrel_all
	v_readlane_b32 s4, v253, 43
	v_readlane_b32 s5, v253, 44
	s_mov_b64 s[38:39], 0
	s_nop 3
	global_load_dword v0, v97, s[4:5] sc1
	s_waitcnt vmcnt(0)
	v_cmp_eq_u32_e32 vcc, v0, v2
	s_and_saveexec_b64 s[36:37], vcc
	s_cbranch_execz .LBB0_625
	s_mov_b32 s2, 1
	s_branch .LBB0_618

.LBB0_628:
	s_or_b64 exec, exec, s[30:31]
	s_mov_b64 s[30:31], exec
	v_mbcnt_lo_u32_b32 v0, s30, 0
	v_mbcnt_hi_u32_b32 v0, s31, v0
	v_cmp_eq_u32_e32 vcc, 0, v0
	s_waitcnt vmcnt(0)
	s_and_saveexec_b64 s[36:37], vcc
	s_cbranch_execz .LBB0_23
	s_bcnt1_i32_b64 s2, s[30:31]
	v_readlane_b32 s4, v253, 39
	v_mov_b32_e32 v0, s2
	v_readlane_b32 s5, v253, 40
	s_nop 4
	s_branch .LBB0_23
